# v20 + packed f32 in attention softmax: v_pk_fma_f32 for (x-m)*log2e and v_pk_add_f32 row-sum (f32, same math)
# baseline (speedup 1.0000x reference)
.LBB0_632:
	v_mov_b32_e32 v212, v201
	s_nop 1
	v_permlane32_swap_b32_e32 v212, v201
	v_max3_f32 v201, v202, v201, v212
	v_mul_f32_e32 v213, 0xbfb8aa3b, v201
	v_mov_b32_e32 v216, 0x3fb8aa3b
	v_pk_fma_f32 v[114:115], v[114:115], v[216:217], v[212:213] op_sel:[0,0,1] op_sel_hi:[1,0,1]
	v_exp_f32_e32 v114, v114
	v_pk_fma_f32 v[116:117], v[116:117], v[216:217], v[212:213] op_sel:[0,0,1] op_sel_hi:[1,0,1]
	v_exp_f32_e32 v115, v115
	v_exp_f32_e32 v116, v116
	v_exp_f32_e32 v117, v117
	v_pk_add_f32 v[214:215], v[114:115], 0 op_sel_hi:[1,0]
	v_cvt_pk_bf16_f32 v114, v114, v115
	v_pk_add_f32 v[214:215], v[116:117], v[214:215]
	v_cvt_pk_bf16_f32 v115, v116, v117
	v_pk_fma_f32 v[116:117], v[118:119], v[216:217], v[212:213] op_sel:[0,0,1] op_sel_hi:[1,0,1]
	v_pk_fma_f32 v[118:119], v[120:121], v[216:217], v[212:213] op_sel:[0,0,1] op_sel_hi:[1,0,1]
	v_exp_f32_e32 v116, v116
	v_exp_f32_e32 v117, v117
	v_exp_f32_e32 v118, v118
	v_exp_f32_e32 v119, v119
	v_pk_add_f32 v[214:215], v[116:117], v[214:215]
	v_cvt_pk_bf16_f32 v116, v116, v117
	v_pk_add_f32 v[214:215], v[118:119], v[214:215]
	v_cvt_pk_bf16_f32 v117, v118, v119
	ds_write2_b64 v195, v[114:115], v[116:117] offset1:2
	v_pk_fma_f32 v[114:115], v[122:123], v[216:217], v[212:213] op_sel:[0,0,1] op_sel_hi:[1,0,1]
	v_exp_f32_e32 v114, v114
	v_pk_fma_f32 v[116:117], v[124:125], v[216:217], v[212:213] op_sel:[0,0,1] op_sel_hi:[1,0,1]
	v_exp_f32_e32 v115, v115
	v_exp_f32_e32 v116, v116
	v_exp_f32_e32 v117, v117
	v_pk_add_f32 v[214:215], v[114:115], v[214:215]
	v_cvt_pk_bf16_f32 v114, v114, v115
	v_pk_add_f32 v[214:215], v[116:117], v[214:215]
	v_cvt_pk_bf16_f32 v115, v116, v117
	v_pk_fma_f32 v[116:117], v[126:127], v[216:217], v[212:213] op_sel:[0,0,1] op_sel_hi:[1,0,1]
	v_exp_f32_e32 v116, v116
	v_fmamk_f32 v119, v128, 0x3fb8aa3b, v213
	v_exp_f32_e32 v117, v117
	v_fmamk_f32 v120, v129, 0x3fb8aa3b, v213
	v_exp_f32_e32 v119, v119
	v_exp_f32_e32 v120, v120
	v_pk_fma_f32 v[98:99], v[98:99], v[216:217], v[212:213] op_sel:[0,0,1] op_sel_hi:[1,0,1]
	v_exp_f32_e32 v98, v98
	v_pk_fma_f32 v[100:101], v[100:101], v[216:217], v[212:213] op_sel:[0,0,1] op_sel_hi:[1,0,1]
	v_exp_f32_e32 v99, v99
	v_exp_f32_e32 v100, v100
	v_exp_f32_e32 v101, v101
	v_pk_add_f32 v[214:215], v[116:117], v[214:215]
	v_cvt_pk_bf16_f32 v116, v116, v117
	v_add_f32_e32 v214, v119, v214
	v_add_f32_e32 v215, v120, v215
	v_cvt_pk_bf16_f32 v117, v119, v120
	ds_write2_b64 v195, v[114:115], v[116:117] offset0:4 offset1:6
	v_pk_add_f32 v[214:215], v[98:99], v[214:215]
	v_cvt_pk_bf16_f32 v98, v98, v99
	v_pk_add_f32 v[214:215], v[100:101], v[214:215]
	v_cvt_pk_bf16_f32 v99, v100, v101
	v_pk_fma_f32 v[100:101], v[102:103], v[216:217], v[212:213] op_sel:[0,0,1] op_sel_hi:[1,0,1]
	v_pk_fma_f32 v[102:103], v[104:105], v[216:217], v[212:213] op_sel:[0,0,1] op_sel_hi:[1,0,1]
	v_exp_f32_e32 v100, v100
	v_exp_f32_e32 v101, v101
	v_exp_f32_e32 v102, v102
	v_exp_f32_e32 v103, v103
	v_pk_add_f32 v[214:215], v[100:101], v[214:215]
	v_cvt_pk_bf16_f32 v100, v100, v101
	v_pk_add_f32 v[214:215], v[102:103], v[214:215]
	v_cvt_pk_bf16_f32 v101, v102, v103
	ds_write2_b64 v195, v[98:99], v[100:101] offset0:8 offset1:10
	v_pk_fma_f32 v[98:99], v[106:107], v[216:217], v[212:213] op_sel:[0,0,1] op_sel_hi:[1,0,1]
	v_exp_f32_e32 v98, v98
	v_exp_f32_e32 v99, v99
	v_pk_fma_f32 v[100:101], v[108:109], v[216:217], v[212:213] op_sel:[0,0,1] op_sel_hi:[1,0,1]
	v_exp_f32_e32 v100, v100
	v_exp_f32_e32 v101, v101
	v_pk_add_f32 v[214:215], v[98:99], v[214:215]
	v_cvt_pk_bf16_f32 v102, v98, v99
	v_pk_fma_f32 v[98:99], v[110:111], v[216:217], v[212:213] op_sel:[0,0,1] op_sel_hi:[1,0,1]
	v_pk_add_f32 v[214:215], v[100:101], v[214:215]
	v_cvt_pk_bf16_f32 v103, v100, v101
	v_exp_f32_e32 v100, v99
	v_fmamk_f32 v99, v112, 0x3fb8aa3b, v213
	v_exp_f32_e32 v98, v98
	v_exp_f32_e32 v101, v99
	v_fmamk_f32 v99, v113, 0x3fb8aa3b, v213
	v_exp_f32_e32 v105, v99
	v_sub_f32_e32 v202, v202, v201
	v_mul_f32_e32 v202, 0x3fb8aa3b, v202
	v_add_f32_e32 v214, v98, v214
	v_add_f32_e32 v215, v100, v215
	v_add_f32_e32 v214, v101, v214
	v_add_f32_e32 v215, v105, v215
	v_add_f32_e32 v99, v214, v215
	v_cvt_pk_bf16_f32 v104, v98, v100
	v_exp_f32_e32 v98, v202
	ds_bpermute_b32 v100, v171, v99
	v_cvt_pk_bf16_f32 v105, v101, v105
	ds_write2_b64 v195, v[102:103], v[104:105] offset0:12 offset1:14
	v_cmp_neq_f32_e32 vcc, 1.0, v98
	s_cbranch_vccz .LBB0_634
	v_pk_mul_f32 v[64:65], v[64:65], v[98:99] op_sel_hi:[1,0]
	v_pk_mul_f32 v[62:63], v[62:63], v[98:99] op_sel_hi:[1,0]
	v_pk_mul_f32 v[60:61], v[60:61], v[98:99] op_sel_hi:[1,0]
	v_pk_mul_f32 v[58:59], v[58:59], v[98:99] op_sel_hi:[1,0]
	v_pk_mul_f32 v[56:57], v[56:57], v[98:99] op_sel_hi:[1,0]
	v_pk_mul_f32 v[54:55], v[54:55], v[98:99] op_sel_hi:[1,0]
	v_pk_mul_f32 v[52:53], v[52:53], v[98:99] op_sel_hi:[1,0]
	v_pk_mul_f32 v[50:51], v[50:51], v[98:99] op_sel_hi:[1,0]
	v_pk_mul_f32 v[48:49], v[48:49], v[98:99] op_sel_hi:[1,0]
	v_pk_mul_f32 v[46:47], v[46:47], v[98:99] op_sel_hi:[1,0]
	v_pk_mul_f32 v[44:45], v[44:45], v[98:99] op_sel_hi:[1,0]
	v_pk_mul_f32 v[42:43], v[42:43], v[98:99] op_sel_hi:[1,0]
	v_pk_mul_f32 v[40:41], v[40:41], v[98:99] op_sel_hi:[1,0]
	v_pk_mul_f32 v[38:39], v[38:39], v[98:99] op_sel_hi:[1,0]
	v_pk_mul_f32 v[36:37], v[36:37], v[98:99] op_sel_hi:[1,0]
	v_pk_mul_f32 v[34:35], v[34:35], v[98:99] op_sel_hi:[1,0]

.LBB0_638:
	v_mov_b32_e32 v102, v101
	s_nop 1
	v_permlane32_swap_b32_e32 v102, v101
	v_max3_f32 v101, v200, v101, v102
	v_mul_f32_e32 v213, 0xbfb8aa3b, v101
	v_mov_b32_e32 v216, 0x3fb8aa3b
	v_pk_fma_f32 v[82:83], v[82:83], v[216:217], v[212:213] op_sel:[0,0,1] op_sel_hi:[1,0,1]
	v_exp_f32_e32 v82, v82
	v_pk_fma_f32 v[84:85], v[84:85], v[216:217], v[212:213] op_sel:[0,0,1] op_sel_hi:[1,0,1]
	v_exp_f32_e32 v83, v83
	v_exp_f32_e32 v84, v84
	v_exp_f32_e32 v85, v85
	v_pk_add_f32 v[214:215], v[82:83], 0 op_sel_hi:[1,0]
	v_cvt_pk_bf16_f32 v82, v82, v83
	v_pk_add_f32 v[214:215], v[84:85], v[214:215]
	v_cvt_pk_bf16_f32 v83, v84, v85
	v_pk_fma_f32 v[84:85], v[86:87], v[216:217], v[212:213] op_sel:[0,0,1] op_sel_hi:[1,0,1]
	v_exp_f32_e32 v84, v84
	v_pk_fma_f32 v[86:87], v[88:89], v[216:217], v[212:213] op_sel:[0,0,1] op_sel_hi:[1,0,1]
	v_exp_f32_e32 v85, v85
	v_exp_f32_e32 v86, v86
	v_exp_f32_e32 v87, v87
	v_pk_add_f32 v[214:215], v[84:85], v[214:215]
	v_cvt_pk_bf16_f32 v84, v84, v85
	v_pk_add_f32 v[214:215], v[86:87], v[214:215]
	v_cvt_pk_bf16_f32 v85, v86, v87
	v_add_u32_e32 v86, 0x1000, v195
	ds_write2_b64 v86, v[82:83], v[84:85] offset0:64 offset1:66
	v_pk_fma_f32 v[82:83], v[90:91], v[216:217], v[212:213] op_sel:[0,0,1] op_sel_hi:[1,0,1]
	v_exp_f32_e32 v82, v82
	v_pk_fma_f32 v[84:85], v[92:93], v[216:217], v[212:213] op_sel:[0,0,1] op_sel_hi:[1,0,1]
	v_exp_f32_e32 v83, v83
	v_exp_f32_e32 v84, v84
	v_exp_f32_e32 v85, v85
	v_pk_add_f32 v[214:215], v[82:83], v[214:215]
	v_cvt_pk_bf16_f32 v82, v82, v83
	v_pk_add_f32 v[214:215], v[84:85], v[214:215]
	v_cvt_pk_bf16_f32 v83, v84, v85
	v_pk_fma_f32 v[84:85], v[94:95], v[216:217], v[212:213] op_sel:[0,0,1] op_sel_hi:[1,0,1]
	v_exp_f32_e32 v84, v84
	v_exp_f32_e32 v85, v85
	v_pk_fma_f32 v[88:89], v[96:97], v[216:217], v[212:213] op_sel:[0,0,1] op_sel_hi:[1,0,1]
	v_exp_f32_e32 v88, v88
	v_exp_f32_e32 v89, v89
	v_pk_fma_f32 v[66:67], v[66:67], v[216:217], v[212:213] op_sel:[0,0,1] op_sel_hi:[1,0,1]
	v_exp_f32_e32 v66, v66
	v_pk_fma_f32 v[68:69], v[68:69], v[216:217], v[212:213] op_sel:[0,0,1] op_sel_hi:[1,0,1]
	v_exp_f32_e32 v67, v67
	v_exp_f32_e32 v68, v68
	v_exp_f32_e32 v69, v69
	v_pk_add_f32 v[214:215], v[84:85], v[214:215]
	v_cvt_pk_bf16_f32 v84, v84, v85
	v_pk_add_f32 v[214:215], v[88:89], v[214:215]
	v_cvt_pk_bf16_f32 v85, v88, v89
	ds_write2_b64 v86, v[82:83], v[84:85] offset0:68 offset1:70
	v_pk_add_f32 v[214:215], v[66:67], v[214:215]
	v_cvt_pk_bf16_f32 v66, v66, v67
	v_pk_add_f32 v[214:215], v[68:69], v[214:215]
	v_cvt_pk_bf16_f32 v67, v68, v69
	v_pk_fma_f32 v[68:69], v[70:71], v[216:217], v[212:213] op_sel:[0,0,1] op_sel_hi:[1,0,1]
	v_pk_fma_f32 v[70:71], v[72:73], v[216:217], v[212:213] op_sel:[0,0,1] op_sel_hi:[1,0,1]
	v_exp_f32_e32 v68, v68
	v_exp_f32_e32 v69, v69
	v_exp_f32_e32 v70, v70
	v_exp_f32_e32 v71, v71
	v_pk_add_f32 v[214:215], v[68:69], v[214:215]
	v_cvt_pk_bf16_f32 v68, v68, v69
	v_pk_add_f32 v[214:215], v[70:71], v[214:215]
	v_cvt_pk_bf16_f32 v69, v70, v71
	ds_write2_b64 v86, v[66:67], v[68:69] offset0:72 offset1:74
	v_pk_fma_f32 v[66:67], v[74:75], v[216:217], v[212:213] op_sel:[0,0,1] op_sel_hi:[1,0,1]
	v_exp_f32_e32 v66, v66
	v_exp_f32_e32 v67, v67
	v_pk_fma_f32 v[68:69], v[76:77], v[216:217], v[212:213] op_sel:[0,0,1] op_sel_hi:[1,0,1]
	v_exp_f32_e32 v68, v68
	v_exp_f32_e32 v69, v69
	v_pk_add_f32 v[214:215], v[66:67], v[214:215]
	v_cvt_pk_bf16_f32 v70, v66, v67
	v_pk_fma_f32 v[66:67], v[78:79], v[216:217], v[212:213] op_sel:[0,0,1] op_sel_hi:[1,0,1]
	v_pk_add_f32 v[214:215], v[68:69], v[214:215]
	v_cvt_pk_bf16_f32 v71, v68, v69
	v_exp_f32_e32 v68, v67
	v_fmamk_f32 v67, v80, 0x3fb8aa3b, v213
	v_exp_f32_e32 v66, v66
	v_exp_f32_e32 v69, v67
	v_fmamk_f32 v67, v81, 0x3fb8aa3b, v213
	v_exp_f32_e32 v73, v67
	v_sub_f32_e32 v102, v200, v101
	v_mul_f32_e32 v102, 0x3fb8aa3b, v102
	v_add_f32_e32 v214, v66, v214
	v_add_f32_e32 v215, v68, v215
	v_add_f32_e32 v214, v69, v214
	v_add_f32_e32 v215, v73, v215
	v_add_f32_e32 v67, v214, v215
	v_cvt_pk_bf16_f32 v72, v66, v68
	v_exp_f32_e32 v66, v102
	ds_bpermute_b32 v68, v171, v67
	v_cvt_pk_bf16_f32 v73, v69, v73
	ds_write2_b64 v86, v[70:71], v[72:73] offset0:76 offset1:78
	v_cmp_neq_f32_e32 vcc, 1.0, v66
	s_cbranch_vccz .LBB0_640
	v_pk_mul_f32 v[32:33], v[32:33], v[66:67] op_sel_hi:[1,0]
	v_pk_mul_f32 v[30:31], v[30:31], v[66:67] op_sel_hi:[1,0]
	v_pk_mul_f32 v[28:29], v[28:29], v[66:67] op_sel_hi:[1,0]
	v_pk_mul_f32 v[26:27], v[26:27], v[66:67] op_sel_hi:[1,0]
	v_pk_mul_f32 v[24:25], v[24:25], v[66:67] op_sel_hi:[1,0]
	v_pk_mul_f32 v[22:23], v[22:23], v[66:67] op_sel_hi:[1,0]
	v_pk_mul_f32 v[20:21], v[20:21], v[66:67] op_sel_hi:[1,0]
	v_pk_mul_f32 v[18:19], v[18:19], v[66:67] op_sel_hi:[1,0]
	v_pk_mul_f32 v[16:17], v[16:17], v[66:67] op_sel_hi:[1,0]
	v_pk_mul_f32 v[14:15], v[14:15], v[66:67] op_sel_hi:[1,0]
	v_pk_mul_f32 v[12:13], v[12:13], v[66:67] op_sel_hi:[1,0]
	v_pk_mul_f32 v[10:11], v[10:11], v[66:67] op_sel_hi:[1,0]
	v_pk_mul_f32 v[8:9], v[8:9], v[66:67] op_sel_hi:[1,0]
	v_pk_mul_f32 v[6:7], v[6:7], v[66:67] op_sel_hi:[1,0]
	v_pk_mul_f32 v[4:5], v[4:5], v[66:67] op_sel_hi:[1,0]
	v_pk_mul_f32 v[2:3], v[2:3], v[66:67] op_sel_hi:[1,0]
